# GU->D seam: the D unit's address block and its 16 residual row loads moved in front of the wave-level barrier that follows the grid barrier, so seven of eight waves request them while the grid barrier
# baseline (speedup 1.0000x reference)
; #define PG8_STAGE(bufoff, gbase, voff) do { _Pragma("unroll") for (int _i = 0; _i < 2; ++_i) \
;         __builtin_amdgcn_global_load_lds((const unsigned*)((const char*)(gbase) + (voff)[_i]), (PG8_LAS unsigned*)(lds + (bufoff) + ldsw + _i * 8192), 16, 0, 0); } while (0)
; template <class Epi, class Sched, bool ALIGN_EPI = false, bool SP2 = false>
; __device__ __forceinline__ void gemm_phase(PG8_LAS unsigned char* lds, const Gemm g, const Sched& S, const Epi& E) {
;     int tid_ = threadIdx.x; asm volatile("" : "+v"(tid_)); const int tid = tid_, wid = __builtin_amdgcn_readfirstlane(tid >> 6), lane = tid & 63, wr = wid >> 2, wc = wid & 3, fr = lane & 15, fq = lane >> 4;
;     const int K = g.K, nt = K / BK;
;     unsigned voffA[2], voffB[2];
; #pragma unroll
;     for (int i = 0; i < 2; ++i) { int R, C; stage_rc(tid * 16 + i * 8192, R, C); const int Rb = Epi::PERM ? ((R & ~31) + perm32(R & 31)) : R;
;         voffA[i] = (unsigned)(R * K + C) * 2u; voffB[i] = (unsigned)(Rb * K + C) * 2u; }
;     const size_t kstep = (size_t)(BK * 2);
;     const size_t hstep = (size_t)HALF * K * 2;
;     const size_t tstep = 2 * hstep;
;     const unsigned ldsw = (unsigned)wid * 1024u;
;     const int aoff = lds_byte(wr * 64 + fr, fq * 8), boff = lds_byte(wc * 32 + fr, fq * 8);
;     ...
;     Unit cur, nxt; int ui = 0;
;     if (!S.next(0, cur)) return;
;     f32x4 acc[2][2][4][2];
;     typename Epi::Pre pre0 = E.issue(cur, wr, wc, fr, fq);
;     bf16x8 At[4][2], B0[2][2], B1[2][2];
;     const char* cA = (const char*)g.A + (size_t)cur.pm * tstep; const char* cB = (const char*)g.Bt + (size_t)cur.pn * tstep;
;     S.a_ready(cur);
;     if constexpr (SP2) {
;         PG8_STAGE(PG8_SB(0, 0), cB, voffB); PG8_STAGE(PG8_SB(0, 1), cB + hstep, voffB); PG8_STAGE(PG8_SA(0, 0), cA, voffA); PG8_STAGE(PG8_SA(0, 1), cA + hstep, voffA);
;     __device__ __forceinline__ Pre issue(const pg8::Unit& u, int wr, int wc, int fr, int fq) const {
;         Pre p; const int row0 = u.pm * 256 + wr * 64 + fr, colb = u.pn * 256 + wc * 32 + 8 * fq;
; #pragma unroll
;         for (int ai = 0; ai < 2; ++ai)
; #pragma unroll
;             for (int m = 0; m < 4; ++m)
; #pragma unroll
;                 for (int bj = 0; bj < 2; ++bj) p.v[ai][m][bj] = *(const u32x4*)(XB + (size_t)(row0 + ai * 128 + m * 16) * DM + colb + bj * 128);
;         return p;
.LBB0_1883:
	s_or_b64 exec, exec, s[4:5]
	v_readlane_b32 s0, v255, 19
	v_readlane_b32 s1, v255, 20
	s_xor_b64 s[42:43], s[0:1], -1
	v_readlane_b32 s0, v252, 59
	s_waitcnt lgkmcnt(0)
	v_mov_b32_e32 v0, v174
	v_readlane_b32 s1, v252, 60
	s_andn2_b64 vcc, exec, s[0:1]
	v_readfirstlane_b32 s0, v0
	s_cbranch_vccz .Ldres_go
	s_barrier
	s_branch .LBB0_1923
.Ldres_go:
	v_lshlrev_b32_e32 v1, 4, v0
	v_add_u32_e32 v2, 0x2000, v1
	v_ashrrev_i32_e32 v3, 31, v2
	v_lshrrev_b32_e32 v3, 22, v3
	v_add_u32_e32 v3, v2, v3
	v_ashrrev_i32_e32 v136, 10, v3
	v_mul_i32_i24_e32 v3, 0x400, v136
	v_sub_u32_e32 v2, v2, v3
	v_lshrrev_b32_e32 v3, 4, v2
	v_bitop3_b32 v2, v3, v2, 32 bitop3:0x6c
	v_ashrrev_i32_e32 v3, 31, v2
	v_lshrrev_b32_e32 v3, 26, v3
	v_readlane_b32 s4, v255, 19
	v_add_u32_e32 v3, v2, v3
	v_lshlrev_b32_e32 v4, 3, v136
	v_readlane_b32 s5, v255, 20
	v_ashrrev_i32_e32 v137, 6, v3
	v_and_b32_e32 v4, -16, v4
	s_and_b64 s[4:5], s[4:5], exec
	v_add_u32_e32 v4, v137, v4
	v_and_b32_e32 v5, 3, v137
	s_mov_b32 s5, 0xffffe0
	v_lshrrev_b32_e32 v6, 2, v4
	v_lshlrev_b32_e32 v7, 1, v4
	v_and_b32_e32 v3, 0xc0, v3
	s_mov_b32 s1, 0x2300000
	v_and_or_b32 v5, v4, s5, v5
	v_and_b32_e32 v6, 4, v6
	v_and_b32_e32 v7, 24, v7
	v_sub_u32_e32 v2, v2, v3
	s_cselect_b32 s1, 0xb00000, s1
	v_readlane_b32 s4, v254, 61
	v_or3_b32 v5, v5, v6, v7
	v_lshlrev_b32_e32 v6, 5, v136
	v_ashrrev_i16_sdwa v2, v176, sext(v2) dst_sel:DWORD dst_unused:UNUSED_PAD src0_sel:DWORD src1_sel:BYTE_0
	s_add_u32 s26, s4, s1
	v_and_b32_e32 v138, 32, v6
	v_bfe_i32 v139, v2, 0, 16
	s_movk_i32 s4, 0xb00
	v_mul_u32_u24_e32 v5, 0xb00, v5
	v_add_u32_e32 v2, v138, v139
	v_mul_lo_u32 v3, v4, s4
	v_add_lshl_u32 v128, v5, v2, 1
	v_add_lshl_u32 v130, v2, v3, 1
	v_bfe_i32 v2, v0, 27, 1
	v_lshrrev_b32_e32 v2, 22, v2
	v_add_u32_e32 v2, v1, v2
	v_and_b32_e32 v2, 0xfffffc00, v2
	v_sub_u32_e32 v1, v1, v2
	v_lshrrev_b32_e32 v2, 4, v1
	v_ashrrev_i32_e32 v3, 31, v0
	v_bitop3_b32 v1, v2, v1, 32 bitop3:0x6c
	v_lshrrev_b32_e32 v3, 26, v3
	v_bfe_u32 v134, v0, 4, 2
	v_and_b32_e32 v68, 15, v0
	v_ashrrev_i32_e32 v2, 31, v1
	v_add_u32_e32 v0, v0, v3
	v_lshrrev_b32_e32 v2, 26, v2
	v_ashrrev_i32_e32 v141, 6, v0
	v_add_u32_e32 v2, v1, v2
	v_lshlrev_b32_e32 v0, 3, v141
	v_ashrrev_i32_e32 v140, 6, v2
	v_and_b32_e32 v0, -16, v0
	v_add_u32_e32 v0, v140, v0
	v_and_b32_e32 v3, 3, v140
	v_lshrrev_b32_e32 v4, 2, v0
	v_lshlrev_b32_e32 v5, 1, v0
	v_and_b32_e32 v2, 0xc0, v2
	v_readlane_b32 s1, v254, 62
	v_and_or_b32 v3, v0, s5, v3
	v_and_b32_e32 v4, 4, v4
	v_and_b32_e32 v5, 24, v5
	v_sub_u32_e32 v1, v1, v2
	s_addc_u32 s27, s1, 0
	s_ashr_i32 s6, s0, 8
	v_or3_b32 v3, v3, v4, v5
	v_lshlrev_b32_e32 v4, 5, v141
	v_ashrrev_i16_sdwa v1, v176, sext(v1) dst_sel:DWORD dst_unused:UNUSED_PAD src0_sel:DWORD src1_sel:BYTE_0
	s_ashr_i32 s1, s0, 6
	s_lshl_b32 s7, s6, 6
	v_and_b32_e32 v151, 32, v4
	v_bfe_i32 v152, v1, 0, 16
	v_mul_lo_u32 v0, v0, s4
	v_readlane_b32 s4, v253, 23
	s_and_b32 s28, s1, 3
	v_add_u32_e32 v1, v151, v152
	s_add_i32 s4, s4, s7
	s_lshl_b32 s29, s1, 10
	s_lshl_b32 s1, s28, 5
	v_add_lshl_u32 v132, v1, v0, 1
	v_or_b32_e32 v0, s4, v68
	v_readlane_b32 s4, v253, 25
	v_lshlrev_b32_e32 v135, 3, v134
	s_or_b32 s4, s4, s1
	v_mul_u32_u24_e32 v3, 0xb00, v3
	v_or_b32_e32 v2, s4, v135
	v_add_lshl_u32 v144, v3, v1, 1
	v_ashrrev_i32_e32 v3, 31, v2
	v_ashrrev_i32_e32 v1, 31, v0
	v_lshl_add_u64 v[2:3], v[2:3], 1, s[10:11]
	v_lshlrev_b64 v[4:5], 11, v[0:1]
	v_lshl_add_u64 v[8:9], v[2:3], 0, v[4:5]
	v_or_b32_e32 v4, 16, v0
	v_ashrrev_i32_e32 v5, 31, v4
	v_lshlrev_b64 v[4:5], 11, v[4:5]
	v_lshl_add_u64 v[4:5], v[2:3], 0, v[4:5]
	global_load_dwordx4 v[60:63], v[8:9], off
	global_load_dwordx4 v[56:59], v[8:9], off offset:256
	global_load_dwordx4 v[52:55], v[4:5], off
	global_load_dwordx4 v[48:51], v[4:5], off offset:256
	v_or_b32_e32 v4, 32, v0
	v_or_b32_e32 v0, 48, v0
	v_ashrrev_i32_e32 v5, 31, v4
	v_ashrrev_i32_e32 v1, 31, v0
	v_lshlrev_b64 v[4:5], 11, v[4:5]
	v_lshlrev_b64 v[0:1], 11, v[0:1]
	v_lshl_add_u64 v[4:5], v[2:3], 0, v[4:5]
	v_lshl_add_u64 v[0:1], v[2:3], 0, v[0:1]
	s_mov_b64 s[4:5], 0x40000
	global_load_dwordx4 v[44:47], v[4:5], off
	global_load_dwordx4 v[40:43], v[4:5], off offset:256
	global_load_dwordx4 v[36:39], v[0:1], off
	global_load_dwordx4 v[28:31], v[0:1], off offset:256
	v_lshl_add_u64 v[0:1], v[8:9], 0, s[4:5]
	s_mov_b32 s4, 0x40000
	v_add_co_u32_e32 v2, vcc, s4, v8
	s_mov_b64 s[4:5], 0x48000
	s_nop 0
	v_addc_co_u32_e32 v3, vcc, 0, v9, vcc
	global_load_dwordx4 v[32:35], v[2:3], off
	global_load_dwordx4 v[20:23], v[0:1], off offset:256
	v_lshl_add_u64 v[0:1], v[8:9], 0, s[4:5]
	s_mov_b32 s4, 0x48000
	v_add_co_u32_e32 v2, vcc, s4, v8
	s_mov_b64 s[4:5], 0x50000
	s_nop 0
	v_addc_co_u32_e32 v3, vcc, 0, v9, vcc
	global_load_dwordx4 v[24:27], v[2:3], off
	global_load_dwordx4 v[12:15], v[0:1], off offset:256
	v_lshl_add_u64 v[0:1], v[8:9], 0, s[4:5]
	s_mov_b32 s4, 0x50000
	v_add_co_u32_e32 v2, vcc, s4, v8
	s_mov_b64 s[4:5], 0x58000
	s_nop 0
	v_addc_co_u32_e32 v3, vcc, 0, v9, vcc
	global_load_dwordx4 v[16:19], v[2:3], off
	global_load_dwordx4 v[4:7], v[0:1], off offset:256
	v_lshl_add_u64 v[0:1], v[8:9], 0, s[4:5]
	s_mov_b32 s4, 0x58000
	v_readlane_b32 s5, v253, 24
	v_add_co_u32_e32 v2, vcc, s4, v8
	s_mul_i32 s4, s5, 0x160000
	s_add_u32 s4, s26, s4
	s_mul_hi_i32 s5, s5, 0x160000
	s_addc_u32 s5, s27, s5
	s_add_i32 s30, s29, 0
	v_addc_co_u32_e32 v3, vcc, 0, v9, vcc
	s_add_i32 m0, s30, 0x10000
	global_load_dwordx4 v[8:11], v[2:3], off
	s_nop 0
	global_load_dwordx4 v[0:3], v[0:1], off offset:256
	s_barrier
	v_readlane_b32 s16, v253, 32
	global_load_lds_dwordx4 v144, s[4:5]
	s_add_i32 m0, s30, 0x12000
	s_add_u32 s24, s4, 0xb0000
	global_load_lds_dwordx4 v128, s[4:5]
	s_addc_u32 s25, s5, 0
	s_add_i32 m0, s30, 0x14000
	v_readlane_b32 s17, v253, 33
	global_load_lds_dwordx4 v144, s[24:25]
	s_add_i32 m0, s30, 0x16000
	s_add_i32 s31, s30, 0x2000
	global_load_lds_dwordx4 v128, s[24:25]
	s_mov_b32 m0, s30
	s_add_i32 s34, s30, 0x4000
	global_load_lds_dwordx4 v132, s[16:17]
	s_mov_b32 m0, s31
	s_add_i32 s35, s30, 0x6000
	global_load_lds_dwordx4 v130, s[16:17]
	v_readlane_b32 s16, v253, 34
	s_mov_b32 m0, s34
	v_readlane_b32 s17, v253, 35
	v_mov_b32_e32 v129, v145
	s_cmp_eq_u32 s6, 1
	v_lshl_add_u64 v[64:65], s[4:5], 0, v[144:145]
	s_cselect_b64 s[44:45], -1, 0
	s_cmp_lg_u32 s6, 1
	global_load_lds_dwordx4 v132, s[16:17]
	s_mov_b32 m0, s35
	v_lshl_add_u64 v[66:67], s[4:5], 0, v[128:129]
	global_load_lds_dwordx4 v130, s[16:17]
	s_cbranch_scc1 .LBB0_1886
	s_barrier
